# mix_post_b rows in the post_a phase: the 14 loads of a row issued together with cloned address arithmetic (was 5 serialized round trips per row)
# speedup vs baseline: 1.0073x; 1.0052x over previous
.LBB0_1535:
	v_lshl_add_u64 v[100:101], s[14:15], 0, v[96:97]
	v_add_co_u32_e32 v98, vcc, 0x33812000, v100
	s_mov_b32 s0, 0x2d772000
	s_nop 1
	v_addc_co_u32_e32 v99, vcc, 0, v101, vcc
	v_add_co_u32_e32 v102, vcc, 0x326f2000, v100
	global_load_dwordx4 v[108:111], v[98:99], off
	s_nop 1
	v_addc_co_u32_e32 v103, vcc, 0, v101, vcc
	global_load_dwordx4 v[112:115], v[102:103], off
	v_add_co_u32_e32 v104, vcc, s5, v100
	s_nop 1
	v_addc_co_u32_e32 v105, vcc, 0, v101, vcc
	global_load_dwordx4 v[116:119], v[104:105], off
	global_load_dwordx4 v[120:123], v[4:5], off offset:16
	global_load_dwordx4 v[124:127], v[4:5], off
	v_add_co_u32_e32 v98, vcc, s3, v100
	s_nop 1
	v_addc_co_u32_e32 v99, vcc, 0, v101, vcc
	global_load_dwordx4 v[128:131], v[98:99], off
	v_add_co_u32_e32 v98, vcc, s0, v100
	s_nop 1
	v_addc_co_u32_e32 v99, vcc, 0, v101, vcc
	global_load_dwordx4 v[132:135], v[98:99], off
	s_mov_b32 s0, 0x2c652000
	v_add_co_u32_e32 v98, vcc, s0, v100
	s_nop 1
	v_addc_co_u32_e32 v99, vcc, 0, v101, vcc
	v_lshl_add_u64 v[100:101], s[6:7], 0, v[96:97]
	s_mov_b32 s0, 0x1ec01000
	v_add_co_u32_e32 v104, vcc, s0, v100
	global_load_dwordx4 v[138:141], v[98:99], off
	s_nop 1
	v_addc_co_u32_e32 v105, vcc, 0, v101, vcc
	s_mov_b32 s0, 0x1ec02000
	v_add_co_u32_e32 v100, vcc, s0, v100
	global_load_dwordx4 v[142:145], v[104:105], off offset:3584
	s_nop 1
	v_addc_co_u32_e32 v101, vcc, 0, v101, vcc
	global_load_dwordx4 v[146:149], v[100:101], off offset:2592
	global_load_dwordx4 v[150:153], v[6:7], off offset:16
	global_load_dwordx4 v[154:157], v[6:7], off
	global_load_dwordx4 v[158:161], v[8:9], off offset:16
	global_load_dwordx4 v[162:165], v[8:9], off
	v_lshl_add_u64 v[10:11], s[14:15], 0, v[96:97]
	v_add_co_u32_e32 v0, vcc, 0x33812000, v10
	s_mov_b32 s0, 0x2d772000
	s_nop 0
	v_addc_co_u32_e32 v1, vcc, 0, v11, vcc
	v_add_co_u32_e32 v12, vcc, 0x326f2000, v10
	s_waitcnt vmcnt(0)
	v_mov_b64_e32 v[0:1], v[108:109]
	v_mov_b64_e32 v[2:3], v[110:111]
	s_nop 0
	v_addc_co_u32_e32 v13, vcc, 0, v11, vcc
	v_mov_b64_e32 v[18:19], v[112:113]
	v_mov_b64_e32 v[20:21], v[114:115]
	s_add_i32 s4, s4, s2
	s_waitcnt vmcnt(1)
	v_lshlrev_b32_e32 v37, 16, v2
	v_lshlrev_b32_e32 v36, 16, v0
	v_and_b32_e32 v39, 0xffff0000, v2
	s_waitcnt vmcnt(0)
	v_lshlrev_b32_e32 v12, 16, v18
	v_and_b32_e32 v13, 0xffff0000, v18
	v_add_co_u32_e32 v18, vcc, s5, v10
	v_lshlrev_b32_e32 v30, 16, v19
	v_and_b32_e32 v31, 0xffff0000, v19
	v_addc_co_u32_e32 v19, vcc, 0, v11, vcc
	v_lshlrev_b32_e32 v32, 16, v20
	v_and_b32_e32 v33, 0xffff0000, v20
	v_lshlrev_b32_e32 v34, 16, v21
	v_and_b32_e32 v35, 0xffff0000, v21
	v_mov_b64_e32 v[18:19], v[116:117]
	v_mov_b64_e32 v[20:21], v[118:119]
	s_nop 0
	v_mov_b64_e32 v[22:23], v[120:121]
	v_mov_b64_e32 v[24:25], v[122:123]
	v_mov_b64_e32 v[26:27], v[124:125]
	v_mov_b64_e32 v[28:29], v[126:127]
	v_and_b32_e32 v38, 0xffff0000, v0
	v_lshlrev_b32_e32 v41, 16, v3
	v_lshlrev_b32_e32 v40, 16, v1
	v_and_b32_e32 v2, 0xffff0000, v1
	v_pk_add_f32 v[0:1], v[36:37], v[38:39]
	v_and_b32_e32 v3, 0xffff0000, v3
	v_pk_add_f32 v[0:1], v[0:1], v[40:41]
	s_nop 0
	v_pk_add_f32 v[0:1], v[0:1], v[2:3]
	s_nop 0
	v_add_f32_e32 v0, v0, v1
	ds_bpermute_b32 v1, v14, v0
	s_waitcnt lgkmcnt(0)
	v_add_f32_e32 v0, v0, v1
	ds_bpermute_b32 v1, v15, v0
	s_waitcnt lgkmcnt(0)
	v_add_f32_e32 v0, v0, v1
	ds_bpermute_b32 v1, v16, v0
	s_waitcnt lgkmcnt(0)
	v_add_f32_e32 v0, v0, v1
	v_fmac_f32_e32 v38, 0xbc800000, v0
	v_fmac_f32_e32 v39, 0xbc800000, v0
	v_fmac_f32_e32 v36, 0xbc800000, v0
	v_fmac_f32_e32 v37, 0xbc800000, v0
	v_mov_b32_e32 v1, v39
	v_mov_b32_e32 v43, v38
	v_pk_mul_f32 v[38:39], v[38:39], v[38:39]
	v_fmac_f32_e32 v2, 0xbc800000, v0
	v_fmac_f32_e32 v40, 0xbc800000, v0
	v_fmac_f32_e32 v3, 0xbc800000, v0
	v_fmac_f32_e32 v41, 0xbc800000, v0
	v_mov_b32_e32 v0, v37
	v_mov_b32_e32 v42, v36
	v_pk_fma_f32 v[36:37], v[36:37], v[36:37], v[38:39]
	v_mov_b32_e32 v39, v3
	v_pk_fma_f32 v[36:37], v[40:41], v[40:41], v[36:37]
	v_mov_b32_e32 v45, v2
	v_pk_fma_f32 v[2:3], v[2:3], v[2:3], v[36:37]
	v_mov_b32_e32 v44, v40
	v_add_f32_e32 v2, v2, v3
	ds_bpermute_b32 v3, v14, v2
	v_mov_b32_e32 v38, v41
	s_waitcnt lgkmcnt(0)
	v_add_f32_e32 v2, v2, v3
	ds_bpermute_b32 v3, v15, v2
	s_waitcnt lgkmcnt(0)
	v_add_f32_e32 v2, v2, v3
	ds_bpermute_b32 v3, v16, v2
	s_waitcnt lgkmcnt(0)
	v_add_f32_e32 v2, v2, v3
	v_fmamk_f32 v2, v2, 0x3c800000, v231
	v_cmp_gt_f32_e32 vcc, s45, v2
	v_mul_f32_e32 v3, 0x4b800000, v2
	s_nop 0
	v_cndmask_b32_e32 v2, v2, v3, vcc
	v_rsq_f32_e32 v2, v2
	s_nop 0
	v_mul_f32_e32 v3, 0x45800000, v2
	v_cndmask_b32_e32 v2, v2, v3, vcc
	v_pk_mul_f32 v[36:37], v[44:45], v[2:3] op_sel_hi:[1,0]
	v_pk_mul_f32 v[40:41], v[42:43], v[2:3] op_sel_hi:[1,0]
	v_pk_mul_f32 v[0:1], v[0:1], v[2:3] op_sel_hi:[1,0]
	s_waitcnt vmcnt(0)
	v_pk_fma_f32 v[12:13], v[26:27], v[40:41], v[12:13]
	v_pk_fma_f32 v[26:27], v[28:29], v[36:37], v[30:31]
	v_pk_mul_f32 v[28:29], v[38:39], v[2:3] op_sel_hi:[1,0]
	v_pk_fma_f32 v[0:1], v[22:23], v[0:1], v[32:33]
	v_pk_fma_f32 v[2:3], v[24:25], v[28:29], v[34:35]
	v_lshlrev_b32_e32 v23, 16, v19
	v_lshlrev_b32_e32 v22, 16, v18
	v_mov_b32_e32 v24, v12
	v_mov_b32_e32 v25, v26
	v_and_b32_e32 v19, 0xffff0000, v19
	v_and_b32_e32 v18, 0xffff0000, v18
	v_mov_b32_e32 v26, v13
	v_pk_mul_f32 v[22:23], v[24:25], v[22:23]
	v_pk_mul_f32 v[12:13], v[26:27], v[18:19]
	v_lshlrev_b32_e32 v19, 16, v21
	v_lshlrev_b32_e32 v18, 16, v20
	v_mov_b32_e32 v25, v2
	v_and_b32_e32 v21, 0xffff0000, v21
	v_and_b32_e32 v20, 0xffff0000, v20
	v_mov_b32_e32 v2, v1
	v_mov_b32_e32 v24, v0
	v_pk_mul_f32 v[0:1], v[2:3], v[20:21]
	v_pk_mul_f32 v[18:19], v[24:25], v[18:19]
	v_bfe_u32 v2, v1, 16, 1
	v_bfe_u32 v3, v0, 16, 1
	v_bfe_u32 v20, v13, 16, 1
	v_bfe_u32 v21, v12, 16, 1
	v_add3_u32 v12, v12, v21, s48
	v_add3_u32 v13, v13, v20, s48
	v_add3_u32 v0, v0, v3, s48
	v_add3_u32 v1, v1, v2, s48
	v_bfe_u32 v2, v22, 16, 1
	v_bfe_u32 v3, v23, 16, 1
	v_bfe_u32 v20, v18, 16, 1
	v_bfe_u32 v21, v19, 16, 1
	v_add3_u32 v19, v19, v21, s48
	v_add3_u32 v18, v18, v20, s48
	v_add3_u32 v3, v23, v3, s48
	v_add3_u32 v2, v22, v2, s48
	v_lshrrev_b32_e32 v20, 16, v2
	v_lshrrev_b32_e32 v21, 16, v3
	v_lshrrev_b32_e32 v2, 16, v18
	v_lshrrev_b32_e32 v3, 16, v19
	v_and_or_b32 v3, v1, s36, v3
	v_and_or_b32 v2, v0, s36, v2
	v_and_or_b32 v1, v13, s36, v21
	v_and_or_b32 v0, v12, s36, v20
	v_lshl_add_u64 v[12:13], s[10:11], 0, v[96:97]
	v_add_co_u32_e32 v12, vcc, s18, v12
	s_add_u32 s10, s10, s12
	s_nop 0
	v_addc_co_u32_e32 v13, vcc, 0, v13, vcc
	global_store_dwordx4 v[12:13], v[0:3], off
	s_addc_u32 s11, s11, s13
	s_add_u32 s14, s14, s16
	v_add_co_u32_e32 v0, vcc, s3, v10
	s_addc_u32 s15, s15, s17
	s_nop 0
	v_addc_co_u32_e32 v1, vcc, 0, v11, vcc
	v_mov_b64_e32 v[0:1], v[128:129]
	v_mov_b64_e32 v[2:3], v[130:131]
	s_waitcnt vmcnt(0)
	v_lshlrev_b32_e32 v42, 16, v0
	v_and_b32_e32 v44, 0xffff0000, v0
	v_add_co_u32_e32 v0, vcc, s0, v10
	v_lshlrev_b32_e32 v43, 16, v1
	v_and_b32_e32 v45, 0xffff0000, v1
	v_addc_co_u32_e32 v1, vcc, 0, v11, vcc
	v_lshlrev_b32_e32 v46, 16, v2
	v_and_b32_e32 v48, 0xffff0000, v2
	v_lshlrev_b32_e32 v47, 16, v3
	v_and_b32_e32 v49, 0xffff0000, v3
	v_mov_b64_e32 v[0:1], v[132:133]
	v_mov_b64_e32 v[2:3], v[134:135]
	s_mov_b32 s0, 0x2c652000
	s_waitcnt vmcnt(0)
	v_lshlrev_b32_e32 v50, 16, v0
	v_and_b32_e32 v52, 0xffff0000, v0
	v_add_co_u32_e32 v0, vcc, s0, v10
	v_lshlrev_b32_e32 v51, 16, v1
	v_and_b32_e32 v53, 0xffff0000, v1
	v_addc_co_u32_e32 v1, vcc, 0, v11, vcc
	v_lshl_add_u64 v[10:11], s[6:7], 0, v[96:97]
	s_mov_b32 s0, 0x1ec01000
	v_add_co_u32_e32 v18, vcc, s0, v10
	v_lshlrev_b32_e32 v54, 16, v2
	v_and_b32_e32 v56, 0xffff0000, v2
	v_lshlrev_b32_e32 v55, 16, v3
	v_and_b32_e32 v57, 0xffff0000, v3
	v_mov_b64_e32 v[0:1], v[138:139]
	v_mov_b64_e32 v[2:3], v[140:141]
	v_addc_co_u32_e32 v19, vcc, 0, v11, vcc
	s_mov_b32 s0, 0x1ec02000
	v_add_co_u32_e32 v10, vcc, s0, v10
	v_mov_b64_e32 v[18:19], v[142:143]
	v_mov_b64_e32 v[20:21], v[144:145]
	s_nop 0
	v_addc_co_u32_e32 v11, vcc, 0, v11, vcc
	v_mov_b64_e32 v[22:23], v[146:147]
	v_mov_b64_e32 v[24:25], v[148:149]
	v_mov_b64_e32 v[26:27], v[150:151]
	v_mov_b64_e32 v[28:29], v[152:153]
	v_mov_b64_e32 v[30:31], v[154:155]
	v_mov_b64_e32 v[32:33], v[156:157]
	v_mov_b64_e32 v[34:35], v[158:159]
	v_mov_b64_e32 v[36:37], v[160:161]
	v_mov_b64_e32 v[38:39], v[162:163]
	v_mov_b64_e32 v[40:41], v[164:165]
	v_pk_add_f32 v[10:11], v[42:43], v[50:51]
	v_pk_add_f32 v[42:43], v[44:45], v[52:53]
	v_mov_b32_e32 v73, v10
	v_mov_b32_e32 v75, v42
	v_mov_b32_e32 v50, v43
	v_mov_b32_e32 v51, v11
	v_pk_mul_f32 v[50:51], v[50:51], v[50:51]
	s_add_u32 s6, s6, s8
	s_addc_u32 s7, s7, s9
	s_cmpk_lt_i32 s4, 0xc00
	s_waitcnt vmcnt(6)
	v_and_b32_e32 v69, 0xffff0000, v1
	v_and_b32_e32 v68, 0xffff0000, v0
	v_mov_b32_e32 v74, v68
	v_pk_mul_f32 v[74:75], v[74:75], v[74:75]
	v_and_b32_e32 v80, 0xffff0000, v2
	s_waitcnt vmcnt(4)
	v_lshlrev_b32_e32 v70, 16, v22
	s_waitcnt vmcnt(3)
	v_mov_b32_e32 v67, v28
	v_mov_b32_e32 v28, v27
	v_lshlrev_b32_e32 v27, 16, v1
	v_mov_b32_e32 v66, v26
	v_lshlrev_b32_e32 v26, 16, v0
	v_mov_b32_e32 v0, v69
	v_mov_b32_e32 v1, v27
	v_pk_mul_f32 v[0:1], v[0:1], v[0:1]
	v_mov_b32_e32 v72, v26
	v_pk_fma_f32 v[72:73], v[72:73], v[72:73], v[74:75]
	v_mov_b32_e32 v74, v1
	v_mul_f32_e32 v1, 0xbfb8aa3b, v70
	v_exp_f32_e32 v1, v1
	v_and_b32_e32 v22, 0xffff0000, v22
	v_mov_b32_e32 v75, v51
	v_pk_add_f32 v[72:73], v[74:75], v[72:73]
	v_add_f32_e32 v1, 1.0, v1
	v_rcp_f32_e32 v74, v1
	v_mul_f32_e32 v1, 0xbfb8aa3b, v22
	v_exp_f32_e32 v1, v1
	v_lshlrev_b32_e32 v71, 16, v23
	v_and_b32_e32 v23, 0xffff0000, v23
	v_lshlrev_b32_e32 v82, 16, v24
	v_add_f32_e32 v1, 1.0, v1
	v_rcp_f32_e32 v76, v1
	v_mul_f32_e32 v1, 0xbfb8aa3b, v71
	v_exp_f32_e32 v1, v1
	v_and_b32_e32 v24, 0xffff0000, v24
	v_lshlrev_b32_e32 v45, 16, v19
	v_lshlrev_b32_e32 v44, 16, v18
	v_add_f32_e32 v1, 1.0, v1
	v_rcp_f32_e32 v75, v1
	v_mul_f32_e32 v1, 0xbfb8aa3b, v23
	v_exp_f32_e32 v1, v1
	v_and_b32_e32 v18, 0xffff0000, v18
	v_mul_f32_e32 v53, 0xbfb8aa3b, v18
	s_waitcnt vmcnt(2)
	v_mov_b32_e32 v60, v30
	v_add_f32_e32 v1, 1.0, v1
	v_rcp_f32_e32 v77, v1
	v_mul_f32_e32 v1, 0xbfb8aa3b, v82
	v_exp_f32_e32 v1, v1
	v_mul_f32_e32 v30, 0xbfb8aa3b, v45
	v_exp_f32_e32 v53, v53
	v_exp_f32_e32 v30, v30
	v_add_f32_e32 v1, 1.0, v1
	v_rcp_f32_e32 v86, v1
	v_mul_f32_e32 v1, 0xbfb8aa3b, v24
	v_exp_f32_e32 v1, v1
	v_lshlrev_b32_e32 v83, 16, v25
	v_and_b32_e32 v19, 0xffff0000, v19
	v_add_f32_e32 v53, 1.0, v53
	v_add_f32_e32 v1, 1.0, v1
	v_rcp_f32_e32 v88, v1
	v_mul_f32_e32 v1, 0xbfb8aa3b, v83
	v_exp_f32_e32 v1, v1
	v_add_f32_e32 v30, 1.0, v30
	v_rcp_f32_e32 v58, v53
	v_rcp_f32_e32 v53, v30
	v_mul_f32_e32 v30, 0xbfb8aa3b, v19
	v_exp_f32_e32 v30, v30
	v_and_b32_e32 v25, 0xffff0000, v25
	v_add_f32_e32 v1, 1.0, v1
	v_rcp_f32_e32 v87, v1
	v_mul_f32_e32 v1, 0xbfb8aa3b, v25
	v_exp_f32_e32 v1, v1
	v_add_f32_e32 v30, 1.0, v30
	v_mov_b32_e32 v61, v32
	v_mov_b32_e32 v32, v31
	v_rcp_f32_e32 v59, v30
	v_pk_add_f32 v[30:31], v[46:47], v[54:55]
	v_pk_add_f32 v[46:47], v[48:49], v[56:57]
	s_waitcnt vmcnt(0)
	v_mov_b32_e32 v78, v38
	v_lshlrev_b32_e32 v38, 16, v2
	v_mov_b32_e32 v54, v46
	v_mov_b32_e32 v55, v30
	v_mov_b32_e32 v79, v40
	v_mov_b32_e32 v40, v39
	v_lshlrev_b32_e32 v39, 16, v3
	v_and_b32_e32 v81, 0xffff0000, v3
	v_mov_b32_e32 v2, v80
	v_mov_b32_e32 v3, v38
	v_add_f32_e32 v1, 1.0, v1
	v_pk_mul_f32 v[54:55], v[54:55], v[54:55]
	v_pk_mul_f32 v[2:3], v[2:3], v[2:3]
	v_rcp_f32_e32 v89, v1
	v_mov_b32_e32 v1, v50
	v_mov_b32_e32 v56, v47
	v_mov_b32_e32 v57, v31
	v_mov_b32_e32 v84, v81
	v_mov_b32_e32 v85, v39
	v_pk_add_f32 v[0:1], v[0:1], v[72:73]
	v_mov_b32_e32 v50, v3
	v_mov_b32_e32 v51, v55
	v_pk_mul_f32 v[56:57], v[56:57], v[56:57]
	v_pk_mul_f32 v[84:85], v[84:85], v[84:85]
	v_pk_add_f32 v[0:1], v[50:51], v[0:1]
	v_mov_b32_e32 v3, v54
	v_pk_add_f32 v[0:1], v[2:3], v[0:1]
	v_mov_b32_e32 v2, v85
	v_mov_b32_e32 v3, v57
	v_pk_add_f32 v[0:1], v[2:3], v[0:1]
	v_mov_b32_e32 v85, v56
	v_pk_add_f32 v[0:1], v[84:85], v[0:1]
	ds_bpermute_b32 v3, v14, v1
	ds_bpermute_b32 v2, v14, v0
	v_lshlrev_b32_e32 v48, 16, v20
	v_and_b32_e32 v20, 0xffff0000, v20
	v_mul_f32_e32 v63, 0xbfb8aa3b, v20
	v_exp_f32_e32 v63, v63
	s_waitcnt lgkmcnt(0)
	v_pk_add_f32 v[0:1], v[0:1], v[2:3]
	ds_bpermute_b32 v3, v15, v1
	ds_bpermute_b32 v2, v15, v0
	v_lshlrev_b32_e32 v49, 16, v21
	v_and_b32_e32 v21, 0xffff0000, v21
	v_add_f32_e32 v63, 1.0, v63
	v_mul_f32_e32 v65, 0xbfb8aa3b, v21
	s_waitcnt lgkmcnt(0)
	v_pk_add_f32 v[0:1], v[0:1], v[2:3]
	ds_bpermute_b32 v3, v16, v1
	ds_bpermute_b32 v2, v16, v0
	v_mul_f32_e32 v52, 0xbfb8aa3b, v44
	v_mul_f32_e32 v62, 0xbfb8aa3b, v48
	v_rcp_f32_e32 v64, v63
	v_mul_f32_e32 v63, 0xbfb8aa3b, v49
	s_waitcnt lgkmcnt(0)
	v_pk_add_f32 v[0:1], v[0:1], v[2:3]
	ds_bpermute_b32 v3, v17, v1
	ds_bpermute_b32 v2, v17, v0
	v_exp_f32_e32 v65, v65
	v_exp_f32_e32 v52, v52
	v_exp_f32_e32 v62, v62
	v_exp_f32_e32 v63, v63
	s_waitcnt lgkmcnt(0)
	v_pk_add_f32 v[0:1], v[0:1], v[2:3]
	v_add_f32_e32 v65, 1.0, v65
	v_pk_fma_f32 v[50:51], v[0:1], s[20:21], v[242:243] op_sel_hi:[1,0,0]
	v_add_f32_e32 v52, 1.0, v52
	v_mul_f32_e32 v0, 0x4b800000, v51
	v_cmp_gt_f32_e64 s[0:1], s45, v51
	v_add_f32_e32 v62, 1.0, v62
	v_add_f32_e32 v63, 1.0, v63
	v_cndmask_b32_e64 v0, v51, v0, s[0:1]
	v_rsq_f32_e32 v0, v0
	v_rcp_f32_e32 v65, v65
	v_rcp_f32_e32 v52, v52
	v_rcp_f32_e32 v62, v62
	v_mul_f32_e32 v1, 0x45800000, v0
	v_cndmask_b32_e64 v0, v0, v1, s[0:1]
	v_pk_mul_f32 v[2:3], v[10:11], v[0:1] op_sel_hi:[1,0]
	v_pk_mul_f32 v[10:11], v[42:43], v[0:1] op_sel_hi:[1,0]
	v_rcp_f32_e32 v63, v63
	v_pk_mul_f32 v[10:11], v[32:33], v[10:11]
	v_pk_mul_f32 v[2:3], v[60:61], v[2:3]
	v_pk_mul_f32 v[10:11], v[10:11], v[18:19]
	v_pk_mul_f32 v[18:19], v[30:31], v[0:1] op_sel_hi:[1,0]
	v_pk_mul_f32 v[0:1], v[46:47], v[0:1] op_sel_hi:[1,0]
	v_pk_mul_f32 v[18:19], v[66:67], v[18:19]
	v_pk_mul_f32 v[0:1], v[28:29], v[0:1]
	v_pk_mul_f32 v[2:3], v[2:3], v[44:45]
	v_pk_mul_f32 v[0:1], v[0:1], v[20:21]
	v_pk_mul_f32 v[10:11], v[58:59], v[10:11]
	v_pk_mul_f32 v[18:19], v[18:19], v[48:49]
	v_pk_mul_f32 v[0:1], v[64:65], v[0:1]
	v_pk_mul_f32 v[2:3], v[52:53], v[2:3]
	v_pk_mul_f32 v[18:19], v[62:63], v[18:19]
	v_bfe_u32 v20, v1, 16, 1
	v_bfe_u32 v21, v0, 16, 1
	v_bfe_u32 v28, v11, 16, 1
	v_bfe_u32 v29, v10, 16, 1
	v_add3_u32 v10, v10, v29, s48
	v_add3_u32 v11, v11, v28, s48
	v_add3_u32 v0, v0, v21, s48
	v_add3_u32 v1, v1, v20, s48
	v_bfe_u32 v20, v2, 16, 1
	v_bfe_u32 v21, v3, 16, 1
	v_bfe_u32 v28, v18, 16, 1
	v_bfe_u32 v29, v19, 16, 1
	v_add3_u32 v19, v19, v29, s48
	v_add3_u32 v18, v18, v28, s48
	v_add3_u32 v3, v3, v21, s48
	v_add3_u32 v2, v2, v20, s48
	v_lshrrev_b32_e32 v20, 16, v2
	v_lshrrev_b32_e32 v21, 16, v3
	v_lshrrev_b32_e32 v2, 16, v18
	v_lshrrev_b32_e32 v3, 16, v19
	v_and_or_b32 v3, v1, s36, v3
	v_and_or_b32 v2, v0, s36, v2
	v_and_or_b32 v1, v11, s36, v21
	v_and_or_b32 v0, v10, s36, v20
	v_cmp_gt_f32_e32 vcc, s45, v50
	global_store_dwordx4 v[12:13], v[0:3], off offset:2048
	v_mov_b32_e32 v21, v36
	v_mov_b32_e32 v36, v35
	v_mul_f32_e32 v0, 0x4b800000, v50
	v_cndmask_b32_e32 v0, v50, v0, vcc
	v_rsq_f32_e32 v0, v0
	v_mov_b32_e32 v20, v34
	v_mul_f32_e32 v1, 0x45800000, v0
	v_cndmask_b32_e32 v0, v0, v1, vcc
	v_pk_mul_f32 v[2:3], v[0:1], v[26:27] op_sel_hi:[0,1]
	v_pk_mul_f32 v[10:11], v[0:1], v[68:69] op_sel_hi:[0,1]
	v_pk_mul_f32 v[18:19], v[0:1], v[38:39] op_sel_hi:[0,1]
	v_pk_mul_f32 v[0:1], v[0:1], v[80:81] op_sel_hi:[0,1]
	v_pk_mul_f32 v[10:11], v[40:41], v[10:11]
	v_pk_mul_f32 v[0:1], v[36:37], v[0:1]
	v_pk_mul_f32 v[2:3], v[78:79], v[2:3]
	v_pk_mul_f32 v[10:11], v[10:11], v[22:23]
	v_pk_mul_f32 v[18:19], v[20:21], v[18:19]
	v_pk_mul_f32 v[0:1], v[0:1], v[24:25]
	v_pk_mul_f32 v[2:3], v[2:3], v[70:71]
	v_pk_mul_f32 v[10:11], v[76:77], v[10:11]
	v_pk_mul_f32 v[18:19], v[18:19], v[82:83]
	v_pk_mul_f32 v[0:1], v[88:89], v[0:1]
	v_pk_mul_f32 v[2:3], v[74:75], v[2:3]
	v_pk_mul_f32 v[18:19], v[86:87], v[18:19]
	v_bfe_u32 v20, v1, 16, 1
	v_bfe_u32 v21, v0, 16, 1
	v_bfe_u32 v22, v11, 16, 1
	v_bfe_u32 v23, v10, 16, 1
	v_add3_u32 v10, v10, v23, s48
	v_add3_u32 v11, v11, v22, s48
	v_add3_u32 v0, v0, v21, s48
	v_add3_u32 v1, v1, v20, s48
	v_bfe_u32 v20, v2, 16, 1
	v_bfe_u32 v21, v3, 16, 1
	v_bfe_u32 v22, v18, 16, 1
	v_bfe_u32 v23, v19, 16, 1
	v_add3_u32 v19, v19, v23, s48
	v_add3_u32 v18, v18, v22, s48
	v_add3_u32 v3, v3, v21, s48
	v_add3_u32 v2, v2, v20, s48
	v_lshrrev_b32_e32 v20, 16, v2
	v_lshrrev_b32_e32 v21, 16, v3
	v_lshrrev_b32_e32 v2, 16, v18
	v_lshrrev_b32_e32 v3, 16, v19
	v_and_or_b32 v3, v1, s36, v3
	v_and_or_b32 v2, v0, s36, v2
	v_and_or_b32 v1, v11, s36, v21
	v_and_or_b32 v0, v10, s36, v20
	global_store_dwordx4 v[12:13], v[0:3], off offset:3072
	s_cbranch_scc1 .LBB0_1535
